# v11 + phase B epilogue: f32->bf16 RNE pack by v_cvt_pk_bf16_f32 (same rounding as the bit trick it replaces)
# speedup vs baseline: 1.0292x; 1.0002x over previous
.LBB0_283:
	s_waitcnt lgkmcnt(0)
	v_mul_hi_u32_u24_e32 v65, s64, v130
	v_mul_u32_u24_e32 v64, s64, v130
	v_lshl_add_u64 v[68:69], v[64:65], 1, v[72:73]
	v_cvt_pk_bf16_f32 v65, v75, v77
	v_cvt_pk_bf16_f32 v64, v74, v76
	v_and_b32_sdwa v67, v78, v202 dst_sel:DWORD dst_unused:UNUSED_PAD src0_sel:WORD_1 src1_sel:DWORD
	v_add3_u32 v70, v78, v67, s63
	v_and_b32_sdwa v71, v80, v202 dst_sel:DWORD dst_unused:UNUSED_PAD src0_sel:WORD_1 src1_sel:DWORD
	v_add3_u32 v71, v80, v71, s63
	v_and_b32_e32 v71, 0xffff0000, v71
	v_cvt_pk_bf16_f32 v67, v79, v81
	v_or_b32_sdwa v66, v70, v71 dst_sel:DWORD dst_unused:UNUSED_PAD src0_sel:WORD_1 src1_sel:DWORD
	s_andn2_b64 vcc, exec, s[76:77]
	global_store_dwordx4 v[68:69], v[64:67], off
	s_cbranch_vccnz .LBB0_287
	s_nop 0
	v_pk_mul_f32 v[64:65], v[74:75], v[74:75]
	v_pk_mul_f32 v[66:67], v[76:77], v[76:77]
	v_pk_mul_f32 v[68:69], v[78:79], v[78:79]
	v_add_f32_e32 v64, v66, v64
	v_add_f32_e32 v64, v65, v64
	v_add_f32_e32 v64, v67, v64
	v_and_b32_e32 v66, 64, v203
	v_pk_mul_f32 v[70:71], v[80:81], v[80:81]
	v_add_f32_e32 v64, v68, v64
	v_xor_b32_e32 v65, 1, v203
	v_add_u32_e32 v66, 64, v66
	v_add_f32_e32 v64, v70, v64
	v_cmp_lt_i32_e32 vcc, v65, v66
	v_add_f32_e32 v64, v69, v64
	v_add_f32_e32 v64, v71, v64
	v_cndmask_b32_e32 v65, v203, v65, vcc
	v_lshlrev_b32_e32 v65, 2, v65
	ds_bpermute_b32 v65, v65, v64
	s_waitcnt lgkmcnt(0)
	v_add_f32_e32 v64, v64, v65
	v_xor_b32_e32 v65, 2, v203
	v_cmp_lt_i32_e32 vcc, v65, v66
	s_nop 1
	v_cndmask_b32_e32 v65, v203, v65, vcc
	v_lshlrev_b32_e32 v65, 2, v65
	ds_bpermute_b32 v65, v65, v64
	s_waitcnt lgkmcnt(0)
	v_add_f32_e32 v64, v64, v65
	v_xor_b32_e32 v65, 4, v203
	v_cmp_lt_i32_e32 vcc, v65, v66
	s_nop 1
	v_cndmask_b32_e32 v65, v203, v65, vcc
	v_lshlrev_b32_e32 v65, 2, v65
	ds_bpermute_b32 v65, v65, v64
	s_waitcnt lgkmcnt(0)
	v_add_f32_e32 v64, v64, v65
	v_xor_b32_e32 v65, 8, v203
	v_cmp_lt_i32_e32 vcc, v65, v66
	s_nop 1
	v_cndmask_b32_e32 v65, v203, v65, vcc
	v_lshlrev_b32_e32 v65, 2, v65
	ds_bpermute_b32 v65, v65, v64
	s_and_saveexec_b64 s[0:1], s[6:7]
	s_cbranch_execz .LBB0_286
	s_waitcnt lgkmcnt(0)
	v_add_f32_e32 v66, v64, v65
	v_lshl_add_u64 v[64:65], v[130:131], 4, s[78:79]
	v_add_co_u32_e32 v64, vcc, 0xeacf000, v64
	s_nop 1
	v_addc_co_u32_e32 v65, vcc, 0, v65, vcc
	global_store_dword v[64:65], v66, off offset:4032

.LBB0_301:
	s_waitcnt lgkmcnt(0)
	v_mul_hi_u32_u24_e32 v65, s64, v74
	v_mul_u32_u24_e32 v64, s64, v74
	v_lshl_add_u64 v[68:69], v[64:65], 1, v[72:73]
	v_cvt_pk_bf16_f32 v65, v77, v79
	v_cvt_pk_bf16_f32 v64, v76, v78
	v_and_b32_sdwa v67, v80, v202 dst_sel:DWORD dst_unused:UNUSED_PAD src0_sel:WORD_1 src1_sel:DWORD
	v_add3_u32 v70, v80, v67, s63
	v_and_b32_sdwa v71, v82, v202 dst_sel:DWORD dst_unused:UNUSED_PAD src0_sel:WORD_1 src1_sel:DWORD
	v_add3_u32 v71, v82, v71, s63
	v_and_b32_e32 v71, 0xffff0000, v71
	v_cvt_pk_bf16_f32 v67, v81, v83
	v_or_b32_sdwa v66, v70, v71 dst_sel:DWORD dst_unused:UNUSED_PAD src0_sel:WORD_1 src1_sel:DWORD
	s_andn2_b64 vcc, exec, s[76:77]
	global_store_dwordx4 v[68:69], v[64:67], off
	s_cbranch_vccnz .LBB0_305
	s_nop 0
	v_pk_mul_f32 v[64:65], v[76:77], v[76:77]
	v_pk_mul_f32 v[66:67], v[78:79], v[78:79]
	v_pk_mul_f32 v[68:69], v[80:81], v[80:81]
	v_add_f32_e32 v64, v66, v64
	v_add_f32_e32 v64, v65, v64
	v_add_f32_e32 v64, v67, v64
	v_and_b32_e32 v66, 64, v203
	v_pk_mul_f32 v[70:71], v[82:83], v[82:83]
	v_add_f32_e32 v64, v68, v64
	v_xor_b32_e32 v65, 1, v203
	v_add_u32_e32 v66, 64, v66
	v_add_f32_e32 v64, v70, v64
	v_cmp_lt_i32_e32 vcc, v65, v66
	v_add_f32_e32 v64, v69, v64
	v_add_f32_e32 v64, v71, v64
	v_cndmask_b32_e32 v65, v203, v65, vcc
	v_lshlrev_b32_e32 v65, 2, v65
	ds_bpermute_b32 v65, v65, v64
	s_waitcnt lgkmcnt(0)
	v_add_f32_e32 v64, v64, v65
	v_xor_b32_e32 v65, 2, v203
	v_cmp_lt_i32_e32 vcc, v65, v66
	s_nop 1
	v_cndmask_b32_e32 v65, v203, v65, vcc
	v_lshlrev_b32_e32 v65, 2, v65
	ds_bpermute_b32 v65, v65, v64
	s_waitcnt lgkmcnt(0)
	v_add_f32_e32 v64, v64, v65
	v_xor_b32_e32 v65, 4, v203
	v_cmp_lt_i32_e32 vcc, v65, v66
	s_nop 1
	v_cndmask_b32_e32 v65, v203, v65, vcc
	v_lshlrev_b32_e32 v65, 2, v65
	ds_bpermute_b32 v65, v65, v64
	s_waitcnt lgkmcnt(0)
	v_add_f32_e32 v64, v64, v65
	v_xor_b32_e32 v65, 8, v203
	v_cmp_lt_i32_e32 vcc, v65, v66
	s_nop 1
	v_cndmask_b32_e32 v65, v203, v65, vcc
	v_lshlrev_b32_e32 v65, 2, v65
	ds_bpermute_b32 v65, v65, v64
	s_and_saveexec_b64 s[80:81], s[6:7]
	s_cbranch_execz .LBB0_304
	v_mov_b32_e32 v75, v131
	s_waitcnt lgkmcnt(0)
	v_add_f32_e32 v66, v64, v65
	v_lshl_add_u64 v[64:65], v[74:75], 4, s[78:79]
	v_add_co_u32_e32 v64, vcc, 0xeacf000, v64
	s_nop 1
	v_addc_co_u32_e32 v65, vcc, 0, v65, vcc
	global_store_dword v[64:65], v66, off offset:4032

.LBB0_337:
	s_waitcnt lgkmcnt(0)
	v_mul_hi_u32_u24_e32 v65, s64, v74
	v_mul_u32_u24_e32 v64, s64, v74
	v_lshl_add_u64 v[68:69], v[64:65], 1, v[72:73]
	v_cvt_pk_bf16_f32 v65, v77, v79
	v_cvt_pk_bf16_f32 v64, v76, v78
	v_and_b32_sdwa v67, v80, v202 dst_sel:DWORD dst_unused:UNUSED_PAD src0_sel:WORD_1 src1_sel:DWORD
	v_add3_u32 v70, v80, v67, s63
	v_and_b32_sdwa v71, v82, v202 dst_sel:DWORD dst_unused:UNUSED_PAD src0_sel:WORD_1 src1_sel:DWORD
	v_add3_u32 v71, v82, v71, s63
	v_and_b32_e32 v71, 0xffff0000, v71
	v_cvt_pk_bf16_f32 v67, v81, v83
	v_or_b32_sdwa v66, v70, v71 dst_sel:DWORD dst_unused:UNUSED_PAD src0_sel:WORD_1 src1_sel:DWORD
	s_andn2_b64 vcc, exec, s[76:77]
	global_store_dwordx4 v[68:69], v[64:67], off
	s_cbranch_vccnz .LBB0_268
	s_nop 0
	v_pk_mul_f32 v[64:65], v[76:77], v[76:77]
	v_pk_mul_f32 v[66:67], v[78:79], v[78:79]
	v_pk_mul_f32 v[68:69], v[80:81], v[80:81]
	v_add_f32_e32 v64, v66, v64
	v_add_f32_e32 v64, v65, v64
	v_add_f32_e32 v64, v67, v64
	v_and_b32_e32 v66, 64, v203
	v_pk_mul_f32 v[70:71], v[82:83], v[82:83]
	v_add_f32_e32 v64, v68, v64
	v_xor_b32_e32 v65, 1, v203
	v_add_u32_e32 v66, 64, v66
	v_add_f32_e32 v64, v70, v64
	v_cmp_lt_i32_e32 vcc, v65, v66
	v_add_f32_e32 v64, v69, v64
	v_add_f32_e32 v64, v71, v64
	v_cndmask_b32_e32 v65, v203, v65, vcc
	v_lshlrev_b32_e32 v65, 2, v65
	ds_bpermute_b32 v65, v65, v64
	s_waitcnt lgkmcnt(0)
	v_add_f32_e32 v64, v64, v65
	v_xor_b32_e32 v65, 2, v203
	v_cmp_lt_i32_e32 vcc, v65, v66
	s_nop 1
	v_cndmask_b32_e32 v65, v203, v65, vcc
	v_lshlrev_b32_e32 v65, 2, v65
	ds_bpermute_b32 v65, v65, v64
	s_waitcnt lgkmcnt(0)
	v_add_f32_e32 v64, v64, v65
	v_xor_b32_e32 v65, 4, v203
	v_cmp_lt_i32_e32 vcc, v65, v66
	s_nop 1
	v_cndmask_b32_e32 v65, v203, v65, vcc
	v_lshlrev_b32_e32 v65, 2, v65
	ds_bpermute_b32 v65, v65, v64
	s_waitcnt lgkmcnt(0)
	v_add_f32_e32 v64, v64, v65
	v_xor_b32_e32 v65, 8, v203
	v_cmp_lt_i32_e32 vcc, v65, v66
	s_nop 1
	v_cndmask_b32_e32 v65, v203, v65, vcc
	v_lshlrev_b32_e32 v65, 2, v65
	ds_bpermute_b32 v65, v65, v64
	s_and_saveexec_b64 s[0:1], s[6:7]
	s_cbranch_execz .LBB0_267
	v_mov_b32_e32 v75, v131
	s_waitcnt lgkmcnt(0)
	v_add_f32_e32 v66, v64, v65
	v_lshl_add_u64 v[64:65], v[74:75], 4, s[78:79]
	v_add_co_u32_e32 v64, vcc, 0xeacf000, v64
	s_nop 1
	v_addc_co_u32_e32 v65, vcc, 0, v65, vcc
	global_store_dword v[64:65], v66, off offset:4032
	s_branch .LBB0_267
